# speedup vs baseline: 1.0066x; 1.0066x over previous
; __device__ __forceinline__ void gemm_tile(const TileDesc& td, char* shm_c, const int wv) {
;     ...
;       int tok = td.bcol + bj * 128 + n * 16 + br_l;
;       int pos = tok & (SEQ - 1);
;       #pragma unroll
;       for (int m = 0; m < 4; ++m) {
;         int i0 = m * 16 + ar_l;
;         const float4* cs = (const float4*)(td.aux + ((long)pos * 128 + i0) * 2);
;         float4 c01 = cs[0], c23 = cs[1];
;         float cc[4] = {c01.x, c01.z, c23.x, c23.z}, ss[4] = {c01.y, c01.w, c23.y, c23.w};
;         f32x4 t1 = acc[0][bj][m][n], t2 = acc[1][bj][m][n], o1, o2;
;         #pragma unroll
;         for (int j = 0; j < 4; ++j) { o1[j] = (t1[j] * cc[j] - t2[j] * ss[j]) * sc; o2[j] = (t2[j] * cc[j] + t1[j] * ss[j]) * sc; }
;         long o = (long)tok * td.ldo + (td.brow + i0);
;         uint2 pk; pk.x = pack2(o1[0], o1[1]); pk.y = pack2(o1[2], o1[3]);
;         *(uint2*)(td.outb + o) = pk;
;         pk.x = pack2(o2[0], o2[1]); pk.y = pack2(o2[2], o2[3]);
;         *(uint2*)(td.outb + o + 128) = pk;
;         if (td.outT) {
;           u16* tp = td.outT + (long)i0 * LDT + tok;
;           #pragma unroll
;           for (int j = 0; j < 4; ++j) {
;             tp[(long)j * LDT] = (u16)(pack2(o1[j], 0.f) & 0xffffu);
;             tp[(long)(j + 128) * LDT] = (u16)(pack2(o2[j], 0.f) & 0xffffu);
;           }
.LBB0_585:
	s_andn2_b64 vcc, exec, s[46:47]
	s_cbranch_vccnz .LBB0_618
	v_or_b32_e32 v128, s50, v164
	v_lshlrev_b32_e32 v129, 7, v128
	v_and_b32_e32 v156, 0x7b780, v129
	v_add_u32_e32 v132, v156, v136
	v_lshl_add_u64 v[130:131], v[132:133], 3, s[40:41]
	v_mov_b32_e32 v236, v130
	v_mov_b32_e32 v237, v131
	v_add_co_u32_e32 v238, vcc, 0x4000, v130
	s_nop 1
	v_addc_co_u32_e32 v239, vcc, 0, v131, vcc
	v_add_co_u32_e32 v240, vcc, 0x20000, v130
	s_nop 1
	v_addc_co_u32_e32 v241, vcc, 0, v131, vcc
	v_add_co_u32_e32 v242, vcc, 0x24000, v130
	s_nop 1
	v_addc_co_u32_e32 v243, vcc, 0, v131, vcc
	global_load_dwordx4 v[172:175], v[236:237], off
	global_load_dwordx4 v[176:179], v[236:237], off offset:16
	global_load_dwordx4 v[180:183], v[236:237], off offset:128
	global_load_dwordx4 v[184:187], v[236:237], off offset:144
	global_load_dwordx4 v[188:191], v[236:237], off offset:256
	global_load_dwordx4 v[192:195], v[236:237], off offset:272
	global_load_dwordx4 v[196:199], v[236:237], off offset:384
	global_load_dwordx4 v[200:203], v[236:237], off offset:400
	global_load_dwordx4 v[204:207], v[238:239], off
	global_load_dwordx4 v[208:211], v[238:239], off offset:16
	global_load_dwordx4 v[212:215], v[238:239], off offset:128
	global_load_dwordx4 v[216:219], v[238:239], off offset:144
	global_load_dwordx4 v[220:223], v[238:239], off offset:256
	global_load_dwordx4 v[224:227], v[238:239], off offset:272
	global_load_dwordx4 v[228:231], v[238:239], off offset:384
	global_load_dwordx4 v[232:235], v[238:239], off offset:400
	v_ashrrev_i32_e32 v129, 31, v128
	v_mul_lo_u32 v132, s35, v128
	v_mad_u64_u32 v[146:147], s[0:1], s34, v128, 0
	v_mul_lo_u32 v135, s34, v129
	v_add_u32_e32 v130, s14, v136
	v_add3_u32 v147, v147, v135, v132
	v_ashrrev_i32_e32 v131, 31, v130
	v_lshl_add_u64 v[146:147], v[146:147], 1, s[36:37]
	v_lshl_add_u64 v[148:149], v[130:131], 1, v[146:147]
	v_mov_b32_e32 v137, v133
	s_cmp_lg_u64 s[42:43], 0
	v_lshlrev_b64 v[150:151], 15, v[136:137]
	s_cselect_b64 s[4:5], -1, 0
	s_cmp_eq_u64 s[42:43], 0
	s_waitcnt vmcnt(14)
	v_mov_b32_e32 v138, v172
	v_mov_b32_e32 v139, v173
	v_mov_b32_e32 v140, v174
	v_mov_b32_e32 v141, v175
	v_mov_b32_e32 v142, v176
	v_mov_b32_e32 v143, v177
	v_mov_b32_e32 v144, v178
	v_mov_b32_e32 v145, v179
	v_mov_b32_e32 v147, v140
	v_mov_b32_e32 v140, v139
	v_mov_b32_e32 v139, v144
	v_mov_b32_e32 v144, v143
	v_mov_b32_e32 v146, v138
	v_mov_b32_e32 v138, v142
	v_pk_mul_f32 v[142:143], v[124:125], v[140:141]
	v_pk_mul_f32 v[140:141], v[60:61], v[140:141]
	v_pk_mul_f32 v[152:153], v[126:127], v[144:145]
	v_pk_mul_f32 v[144:145], v[62:63], v[144:145]
	v_pk_fma_f32 v[142:143], v[60:61], v[146:147], v[142:143]
	v_pk_fma_f32 v[140:141], v[124:125], v[146:147], v[140:141] neg_lo:[0,0,1] neg_hi:[0,0,1]
	v_pk_fma_f32 v[152:153], v[62:63], v[138:139], v[152:153]
	v_pk_fma_f32 v[138:139], v[126:127], v[138:139], v[144:145] neg_lo:[0,0,1] neg_hi:[0,0,1]
	v_pk_mul_f32 v[144:145], v[134:135], v[142:143] op_sel_hi:[0,1]
	v_pk_mul_f32 v[146:147], v[134:135], v[140:141] op_sel_hi:[0,1]
	v_pk_mul_f32 v[142:143], v[134:135], v[138:139] op_sel_hi:[0,1]
	v_pk_mul_f32 v[140:141], v[134:135], v[152:153] op_sel_hi:[0,1]
	v_cvt_pk_bf16_f32 v138, v146, v147
	v_cvt_pk_bf16_f32 v139, v142, v143
	v_cvt_pk_bf16_f32 v152, v144, v145
	v_cvt_pk_bf16_f32 v153, v140, v141
	global_store_dwordx2 v[148:149], v[138:139], off
	global_store_dwordx2 v[148:149], v[152:153], off offset:256
	v_lshl_add_u64 v[138:139], s[42:43], 0, v[150:151]
	s_cbranch_scc1 .LBB0_588
	v_lshl_add_u64 v[150:151], v[128:129], 1, v[138:139]
	v_add_co_u32_e32 v152, vcc, 0x400000, v150
	v_cvt_pk_bf16_f32 v132, v146, s0
	s_nop 0
	v_addc_co_u32_e32 v153, vcc, 0, v151, vcc
	global_store_short v[150:151], v132, off
	v_cvt_pk_bf16_f32 v132, v144, s0
	v_add_co_u32_e32 v146, vcc, 0x8000, v150
	global_store_short v[152:153], v132, off
	v_cvt_pk_bf16_f32 v132, v147, s0
	v_addc_co_u32_e32 v147, vcc, 0, v151, vcc
	v_add_co_u32_e32 v144, vcc, 0x408000, v150
	global_store_short v[146:147], v132, off
	v_cvt_pk_bf16_f32 v132, v145, s0
	v_addc_co_u32_e32 v145, vcc, 0, v151, vcc
	global_store_short v[144:145], v132, off
	v_add_co_u32_e32 v144, vcc, s66, v150
	v_cvt_pk_bf16_f32 v132, v142, s0
	s_nop 0
	v_addc_co_u32_e32 v145, vcc, 0, v151, vcc
	global_store_short v[144:145], v132, off
	v_add_co_u32_e32 v144, vcc, 0x410000, v150
	v_cvt_pk_bf16_f32 v132, v140, s0
	s_nop 0
	v_addc_co_u32_e32 v145, vcc, 0, v151, vcc
	v_add_co_u32_e32 v142, vcc, 0x18000, v150
	global_store_short v[144:145], v132, off
	v_cvt_pk_bf16_f32 v132, v143, s0
	v_addc_co_u32_e32 v143, vcc, 0, v151, vcc
	v_add_co_u32_e32 v140, vcc, 0x418000, v150
	global_store_short v[142:143], v132, off
	v_cvt_pk_bf16_f32 v132, v141, s0
	v_addc_co_u32_e32 v141, vcc, 0, v151, vcc
	global_store_short v[140:141], v132, off
; __device__ __forceinline__ void gemm_tile(const TileDesc& td, char* shm_c, const int wv) {
;     ...
;       int tok = td.bcol + bj * 128 + n * 16 + br_l;
;       int pos = tok & (SEQ - 1);
;       #pragma unroll
;       for (int m = 0; m < 4; ++m) {
;         int i0 = m * 16 + ar_l;
;         const float4* cs = (const float4*)(td.aux + ((long)pos * 128 + i0) * 2);
;         float4 c01 = cs[0], c23 = cs[1];
;         float cc[4] = {c01.x, c01.z, c23.x, c23.z}, ss[4] = {c01.y, c01.w, c23.y, c23.w};
;         f32x4 t1 = acc[0][bj][m][n], t2 = acc[1][bj][m][n], o1, o2;
;         #pragma unroll
;         for (int j = 0; j < 4; ++j) { o1[j] = (t1[j] * cc[j] - t2[j] * ss[j]) * sc; o2[j] = (t2[j] * cc[j] + t1[j] * ss[j]) * sc; }
;         long o = (long)tok * td.ldo + (td.brow + i0);
;         uint2 pk; pk.x = pack2(o1[0], o1[1]); pk.y = pack2(o1[2], o1[3]);
;         *(uint2*)(td.outb + o) = pk;
;         pk.x = pack2(o2[0], o2[1]); pk.y = pack2(o2[2], o2[3]);
;         *(uint2*)(td.outb + o + 128) = pk;
;         if (td.outT) {
;           u16* tp = td.outT + (long)i0 * LDT + tok;
;           #pragma unroll
;           for (int j = 0; j < 4; ++j) {
;             tp[(long)j * LDT] = (u16)(pack2(o1[j], 0.f) & 0xffffu);
;             tp[(long)(j + 128) * LDT] = (u16)(pack2(o2[j], 0.f) & 0xffffu);
;           }
.LBB0_588:
	v_or_b32_e32 v132, 16, v136
	v_add_u32_e32 v140, v156, v132
	v_mov_b32_e32 v141, v133
	v_lshl_add_u64 v[144:145], v[140:141], 3, s[40:41]
	s_nop 0
	v_mov_b32_e32 v135, v134
	v_cndmask_b32_e64 v137, 0, 1, s[4:5]
	v_lshlrev_b64 v[152:153], 15, v[132:133]
	v_cmp_ne_u32_e64 s[0:1], 1, v137
	s_andn2_b64 vcc, exec, s[4:5]
	s_waitcnt vmcnt(14)
	v_mov_b32_e32 v140, v180
	v_mov_b32_e32 v141, v181
	v_mov_b32_e32 v142, v182
	v_mov_b32_e32 v143, v183
	v_mov_b32_e32 v144, v184
	v_mov_b32_e32 v145, v185
	v_mov_b32_e32 v146, v186
	v_mov_b32_e32 v147, v187
	v_mov_b32_e32 v151, v142
	v_mov_b32_e32 v142, v141
	v_mov_b32_e32 v141, v146
	v_mov_b32_e32 v146, v145
	v_mov_b32_e32 v150, v140
	v_mov_b32_e32 v140, v144
	v_pk_mul_f32 v[144:145], v[116:117], v[142:143]
	v_pk_mul_f32 v[142:143], v[52:53], v[142:143]
	v_pk_mul_f32 v[154:155], v[118:119], v[146:147]
	v_pk_mul_f32 v[146:147], v[54:55], v[146:147]
	v_pk_fma_f32 v[144:145], v[52:53], v[150:151], v[144:145]
	v_pk_fma_f32 v[142:143], v[116:117], v[150:151], v[142:143] neg_lo:[0,0,1] neg_hi:[0,0,1]
	v_pk_fma_f32 v[154:155], v[54:55], v[140:141], v[154:155]
	v_pk_fma_f32 v[140:141], v[118:119], v[140:141], v[146:147] neg_lo:[0,0,1] neg_hi:[0,0,1]
	v_pk_mul_f32 v[146:147], v[134:135], v[144:145]
	v_pk_mul_f32 v[150:151], v[134:135], v[142:143]
	v_pk_mul_f32 v[144:145], v[134:135], v[140:141]
	v_pk_mul_f32 v[142:143], v[134:135], v[154:155]
	v_cvt_pk_bf16_f32 v140, v150, v151
	v_cvt_pk_bf16_f32 v141, v144, v145
	v_cvt_pk_bf16_f32 v154, v146, v147
	v_cvt_pk_bf16_f32 v155, v142, v143
	global_store_dwordx2 v[148:149], v[140:141], off offset:32
	global_store_dwordx2 v[148:149], v[154:155], off offset:288
	v_lshl_add_u64 v[140:141], s[42:43], 0, v[152:153]
	s_cbranch_vccnz .LBB0_590
	v_lshl_add_u64 v[152:153], v[128:129], 1, v[140:141]
	v_add_co_u32_e32 v154, vcc, 0x400000, v152
	v_cvt_pk_bf16_f32 v137, v150, s0
	s_nop 0
	v_addc_co_u32_e32 v155, vcc, 0, v153, vcc
	global_store_short v[152:153], v137, off
	v_cvt_pk_bf16_f32 v137, v146, s0
	v_add_co_u32_e32 v150, vcc, 0x8000, v152
	global_store_short v[154:155], v137, off
	v_cvt_pk_bf16_f32 v137, v151, s0
	v_addc_co_u32_e32 v151, vcc, 0, v153, vcc
	v_add_co_u32_e32 v146, vcc, 0x408000, v152
	global_store_short v[150:151], v137, off
	v_cvt_pk_bf16_f32 v137, v147, s0
	v_addc_co_u32_e32 v147, vcc, 0, v153, vcc
	global_store_short v[146:147], v137, off
	v_add_co_u32_e32 v146, vcc, s66, v152
	v_cvt_pk_bf16_f32 v137, v144, s0
	s_nop 0
	v_addc_co_u32_e32 v147, vcc, 0, v153, vcc
	global_store_short v[146:147], v137, off
	v_add_co_u32_e32 v146, vcc, 0x410000, v152
	v_cvt_pk_bf16_f32 v137, v142, s0
	s_nop 0
	v_addc_co_u32_e32 v147, vcc, 0, v153, vcc
	v_add_co_u32_e32 v144, vcc, 0x18000, v152
	global_store_short v[146:147], v137, off
	v_cvt_pk_bf16_f32 v137, v145, s0
	v_addc_co_u32_e32 v145, vcc, 0, v153, vcc
	v_add_co_u32_e32 v142, vcc, 0x418000, v152
	global_store_short v[144:145], v137, off
	v_cvt_pk_bf16_f32 v137, v143, s0
	v_addc_co_u32_e32 v143, vcc, 0, v153, vcc
	global_store_short v[142:143], v137, off
.LBB0_590:
	v_or_b32_e32 v142, 32, v136
	v_add_u32_e32 v144, v156, v142
	v_mov_b32_e32 v145, v133
	v_lshl_add_u64 v[150:151], v[144:145], 3, s[40:41]
	s_nop 0
	v_mov_b32_e32 v143, v133
	v_lshlrev_b64 v[158:159], 15, v[142:143]
	s_and_b64 vcc, exec, s[0:1]
	s_waitcnt vmcnt(14)
	v_mov_b32_e32 v144, v188
	v_mov_b32_e32 v145, v189
	v_mov_b32_e32 v146, v190
	v_mov_b32_e32 v147, v191
	v_mov_b32_e32 v150, v192
	v_mov_b32_e32 v151, v193
	v_mov_b32_e32 v152, v194
	v_mov_b32_e32 v153, v195
	v_mov_b32_e32 v155, v146
	v_mov_b32_e32 v146, v145
	v_mov_b32_e32 v145, v152
	v_mov_b32_e32 v152, v151
	v_mov_b32_e32 v154, v144
	v_mov_b32_e32 v144, v150
	v_pk_mul_f32 v[150:151], v[108:109], v[146:147]
	v_pk_mul_f32 v[146:147], v[44:45], v[146:147]
	v_pk_mul_f32 v[166:167], v[110:111], v[152:153]
	v_pk_mul_f32 v[152:153], v[46:47], v[152:153]
	v_pk_fma_f32 v[150:151], v[44:45], v[154:155], v[150:151]
	v_pk_fma_f32 v[146:147], v[108:109], v[154:155], v[146:147] neg_lo:[0,0,1] neg_hi:[0,0,1]
	v_pk_fma_f32 v[166:167], v[46:47], v[144:145], v[166:167]
	v_pk_fma_f32 v[144:145], v[110:111], v[144:145], v[152:153] neg_lo:[0,0,1] neg_hi:[0,0,1]
	v_pk_mul_f32 v[152:153], v[134:135], v[150:151]
	v_pk_mul_f32 v[154:155], v[134:135], v[146:147]
	v_pk_mul_f32 v[150:151], v[134:135], v[144:145]
	v_pk_mul_f32 v[146:147], v[134:135], v[166:167]
	v_cvt_pk_bf16_f32 v144, v154, v155
	v_cvt_pk_bf16_f32 v145, v150, v151
	v_cvt_pk_bf16_f32 v166, v152, v153
	v_cvt_pk_bf16_f32 v167, v146, v147
	global_store_dwordx2 v[148:149], v[144:145], off offset:64
	global_store_dwordx2 v[148:149], v[166:167], off offset:320
	v_lshl_add_u64 v[144:145], s[42:43], 0, v[158:159]
	s_cbranch_vccnz .LBB0_592
	v_lshl_add_u64 v[158:159], v[128:129], 1, v[144:145]
	v_add_co_u32_e32 v166, vcc, 0x400000, v158
	v_cvt_pk_bf16_f32 v137, v154, s0
	s_nop 0
	v_addc_co_u32_e32 v167, vcc, 0, v159, vcc
	global_store_short v[158:159], v137, off
	v_cvt_pk_bf16_f32 v137, v152, s0
	v_add_co_u32_e32 v154, vcc, 0x8000, v158
	global_store_short v[166:167], v137, off
	v_cvt_pk_bf16_f32 v137, v155, s0
	v_addc_co_u32_e32 v155, vcc, 0, v159, vcc
	v_add_co_u32_e32 v152, vcc, 0x408000, v158
	global_store_short v[154:155], v137, off
	v_cvt_pk_bf16_f32 v137, v153, s0
	v_addc_co_u32_e32 v153, vcc, 0, v159, vcc
	global_store_short v[152:153], v137, off
	v_add_co_u32_e32 v152, vcc, s66, v158
	v_cvt_pk_bf16_f32 v137, v150, s0
	s_nop 0
	v_addc_co_u32_e32 v153, vcc, 0, v159, vcc
	global_store_short v[152:153], v137, off
	v_add_co_u32_e32 v152, vcc, 0x410000, v158
	v_cvt_pk_bf16_f32 v137, v146, s0
	s_nop 0
	v_addc_co_u32_e32 v153, vcc, 0, v159, vcc
	v_add_co_u32_e32 v150, vcc, 0x18000, v158
	global_store_short v[152:153], v137, off
	v_cvt_pk_bf16_f32 v137, v151, s0
	v_addc_co_u32_e32 v151, vcc, 0, v159, vcc
	v_add_co_u32_e32 v146, vcc, 0x418000, v158
	global_store_short v[150:151], v137, off
	v_cvt_pk_bf16_f32 v137, v147, s0
	v_addc_co_u32_e32 v147, vcc, 0, v159, vcc
	global_store_short v[146:147], v137, off
; __device__ __forceinline__ void gemm_tile(const TileDesc& td, char* shm_c, const int wv) {
;     ...
;       int tok = td.bcol + bj * 128 + n * 16 + br_l;
;       int pos = tok & (SEQ - 1);
;       #pragma unroll
;       for (int m = 0; m < 4; ++m) {
;         int i0 = m * 16 + ar_l;
;         const float4* cs = (const float4*)(td.aux + ((long)pos * 128 + i0) * 2);
;         float4 c01 = cs[0], c23 = cs[1];
;         float cc[4] = {c01.x, c01.z, c23.x, c23.z}, ss[4] = {c01.y, c01.w, c23.y, c23.w};
;         f32x4 t1 = acc[0][bj][m][n], t2 = acc[1][bj][m][n], o1, o2;
;         #pragma unroll
;         for (int j = 0; j < 4; ++j) { o1[j] = (t1[j] * cc[j] - t2[j] * ss[j]) * sc; o2[j] = (t2[j] * cc[j] + t1[j] * ss[j]) * sc; }
;         long o = (long)tok * td.ldo + (td.brow + i0);
;         uint2 pk; pk.x = pack2(o1[0], o1[1]); pk.y = pack2(o1[2], o1[3]);
;         *(uint2*)(td.outb + o) = pk;
;         pk.x = pack2(o2[0], o2[1]); pk.y = pack2(o2[2], o2[3]);
;         *(uint2*)(td.outb + o + 128) = pk;
;         if (td.outT) {
;           u16* tp = td.outT + (long)i0 * LDT + tok;
;           #pragma unroll
;           for (int j = 0; j < 4; ++j) {
;             tp[(long)j * LDT] = (u16)(pack2(o1[j], 0.f) & 0xffffu);
;             tp[(long)(j + 128) * LDT] = (u16)(pack2(o2[j], 0.f) & 0xffffu);
;           }
.LBB0_592:
	v_or_b32_e32 v146, 48, v136
	v_add_u32_e32 v150, v156, v146
	v_mov_b32_e32 v151, v133
	v_lshl_add_u64 v[154:155], v[150:151], 3, s[40:41]
	s_nop 0
	v_mov_b32_e32 v147, v133
	v_lshlrev_b64 v[158:159], 15, v[146:147]
	s_and_b64 vcc, exec, s[0:1]
	s_waitcnt vmcnt(14)
	v_mov_b32_e32 v150, v196
	v_mov_b32_e32 v151, v197
	v_mov_b32_e32 v152, v198
	v_mov_b32_e32 v153, v199
	v_mov_b32_e32 v154, v200
	v_mov_b32_e32 v155, v201
	v_mov_b32_e32 v156, v202
	v_mov_b32_e32 v157, v203
	v_mov_b32_e32 v167, v152
	v_mov_b32_e32 v152, v151
	v_mov_b32_e32 v151, v156
	v_mov_b32_e32 v156, v155
	v_mov_b32_e32 v166, v150
	v_mov_b32_e32 v150, v154
	v_pk_mul_f32 v[154:155], v[100:101], v[152:153]
	v_pk_mul_f32 v[152:153], v[36:37], v[152:153]
	v_pk_mul_f32 v[168:169], v[102:103], v[156:157]
	v_pk_mul_f32 v[156:157], v[38:39], v[156:157]
	v_pk_fma_f32 v[154:155], v[36:37], v[166:167], v[154:155]
	v_pk_fma_f32 v[152:153], v[100:101], v[166:167], v[152:153] neg_lo:[0,0,1] neg_hi:[0,0,1]
	v_pk_fma_f32 v[166:167], v[38:39], v[150:151], v[168:169]
	v_pk_fma_f32 v[168:169], v[102:103], v[150:151], v[156:157] neg_lo:[0,0,1] neg_hi:[0,0,1]
	v_pk_mul_f32 v[156:157], v[134:135], v[152:153]
	v_pk_mul_f32 v[152:153], v[134:135], v[168:169]
	v_pk_mul_f32 v[154:155], v[134:135], v[154:155]
	v_pk_mul_f32 v[150:151], v[134:135], v[166:167]
	v_cvt_pk_bf16_f32 v166, v156, v157
	v_cvt_pk_bf16_f32 v167, v152, v153
	v_cvt_pk_bf16_f32 v168, v154, v155
	v_cvt_pk_bf16_f32 v169, v150, v151
	global_store_dwordx2 v[148:149], v[166:167], off offset:96
	global_store_dwordx2 v[148:149], v[168:169], off offset:352
	v_lshl_add_u64 v[148:149], s[42:43], 0, v[158:159]
	s_cbranch_vccnz .LBB0_594
	v_lshl_add_u64 v[158:159], v[128:129], 1, v[148:149]
	v_add_co_u32_e32 v166, vcc, 0x400000, v158
	v_cvt_pk_bf16_f32 v137, v156, s0
	s_nop 0
	v_addc_co_u32_e32 v167, vcc, 0, v159, vcc
	global_store_short v[158:159], v137, off
	v_cvt_pk_bf16_f32 v137, v154, s0
	v_add_co_u32_e32 v156, vcc, 0x8000, v158
	global_store_short v[166:167], v137, off
	v_cvt_pk_bf16_f32 v137, v157, s0
	v_addc_co_u32_e32 v157, vcc, 0, v159, vcc
	v_add_co_u32_e32 v154, vcc, 0x408000, v158
	global_store_short v[156:157], v137, off
	v_cvt_pk_bf16_f32 v137, v155, s0
	v_addc_co_u32_e32 v155, vcc, 0, v159, vcc
	global_store_short v[154:155], v137, off
	v_add_co_u32_e32 v154, vcc, s66, v158
	v_cvt_pk_bf16_f32 v137, v152, s0
	s_nop 0
	v_addc_co_u32_e32 v155, vcc, 0, v159, vcc
	global_store_short v[154:155], v137, off
	v_add_co_u32_e32 v154, vcc, 0x410000, v158
	v_cvt_pk_bf16_f32 v137, v150, s0
	s_nop 0
	v_addc_co_u32_e32 v155, vcc, 0, v159, vcc
	v_add_co_u32_e32 v152, vcc, 0x18000, v158
	global_store_short v[154:155], v137, off
	v_cvt_pk_bf16_f32 v137, v153, s0
	v_addc_co_u32_e32 v153, vcc, 0, v159, vcc
	v_add_co_u32_e32 v150, vcc, 0x418000, v158
	global_store_short v[152:153], v137, off
	v_cvt_pk_bf16_f32 v137, v151, s0
	v_addc_co_u32_e32 v151, vcc, 0, v159, vcc
	global_store_short v[150:151], v137, off
.LBB0_594:
	v_or_b32_e32 v147, 16, v128
	v_lshlrev_b32_e32 v137, 7, v147
	v_and_b32_e32 v143, 0x7ff80, v137
	v_add_u32_e32 v150, v143, v136
	v_mov_b32_e32 v151, v133
	v_lshl_add_u64 v[150:151], v[150:151], 3, s[40:41]
	v_mul_lo_u32 v137, s34, v129
	v_mul_lo_u32 v165, s35, v147
	v_mad_u64_u32 v[150:151], s[2:3], s34, v147, 0
	v_add3_u32 v151, v151, v137, v165
	v_lshl_add_u64 v[150:151], v[150:151], 1, s[36:37]
	s_and_b64 vcc, exec, s[0:1]
	v_lshl_add_u64 v[150:151], v[130:131], 1, v[150:151]
	s_waitcnt vmcnt(14)
	v_mov_b32_e32 v152, v204
	v_mov_b32_e32 v153, v205
	v_mov_b32_e32 v154, v206
	v_mov_b32_e32 v155, v207
	v_mov_b32_e32 v156, v208
	v_mov_b32_e32 v157, v209
	v_mov_b32_e32 v158, v210
	v_mov_b32_e32 v159, v211
	v_mov_b32_e32 v167, v154
	v_mov_b32_e32 v154, v153
	v_mov_b32_e32 v153, v158
	v_mov_b32_e32 v158, v157
	v_mov_b32_e32 v166, v152
	v_mov_b32_e32 v152, v156
	v_pk_mul_f32 v[156:157], v[120:121], v[154:155]
	v_pk_mul_f32 v[154:155], v[56:57], v[154:155]
	v_pk_mul_f32 v[168:169], v[122:123], v[158:159]
	v_pk_mul_f32 v[158:159], v[58:59], v[158:159]
	v_pk_fma_f32 v[156:157], v[56:57], v[166:167], v[156:157]
	v_pk_fma_f32 v[154:155], v[120:121], v[166:167], v[154:155] neg_lo:[0,0,1] neg_hi:[0,0,1]
	v_pk_fma_f32 v[166:167], v[58:59], v[152:153], v[168:169]
	v_pk_fma_f32 v[168:169], v[122:123], v[152:153], v[158:159] neg_lo:[0,0,1] neg_hi:[0,0,1]
	v_pk_mul_f32 v[158:159], v[134:135], v[154:155]
	v_pk_mul_f32 v[154:155], v[134:135], v[168:169]
	v_pk_mul_f32 v[156:157], v[134:135], v[156:157]
	v_pk_mul_f32 v[152:153], v[134:135], v[166:167]
	v_cvt_pk_bf16_f32 v166, v158, v159
	v_cvt_pk_bf16_f32 v167, v154, v155
	v_cvt_pk_bf16_f32 v168, v156, v157
	v_cvt_pk_bf16_f32 v169, v152, v153
	global_store_dwordx2 v[150:151], v[166:167], off
	global_store_dwordx2 v[150:151], v[168:169], off offset:256
	s_cbranch_vccnz .LBB0_596
	v_lshl_add_u64 v[166:167], v[128:129], 1, v[138:139]
	v_add_co_u32_e32 v168, vcc, 0x400000, v166
	v_cvt_pk_bf16_f32 v147, v158, s0
	s_nop 0
	v_addc_co_u32_e32 v169, vcc, 0, v167, vcc
	global_store_short v[166:167], v147, off offset:32
	v_cvt_pk_bf16_f32 v147, v156, s0
	v_add_co_u32_e32 v158, vcc, 0x8000, v166
	global_store_short v[168:169], v147, off offset:32
	v_cvt_pk_bf16_f32 v147, v159, s0
	v_addc_co_u32_e32 v159, vcc, 0, v167, vcc
	v_add_co_u32_e32 v156, vcc, 0x408000, v166
	global_store_short v[158:159], v147, off offset:32
	v_cvt_pk_bf16_f32 v147, v157, s0
	v_addc_co_u32_e32 v157, vcc, 0, v167, vcc
	global_store_short v[156:157], v147, off offset:32
	v_add_co_u32_e32 v156, vcc, s66, v166
	v_cvt_pk_bf16_f32 v147, v154, s0
	s_nop 0
	v_addc_co_u32_e32 v157, vcc, 0, v167, vcc
	global_store_short v[156:157], v147, off offset:32
	v_add_co_u32_e32 v156, vcc, 0x410000, v166
	v_cvt_pk_bf16_f32 v147, v152, s0
	s_nop 0
	v_addc_co_u32_e32 v157, vcc, 0, v167, vcc
	v_add_co_u32_e32 v154, vcc, 0x18000, v166
	global_store_short v[156:157], v147, off offset:32
	v_cvt_pk_bf16_f32 v147, v155, s0
	v_addc_co_u32_e32 v155, vcc, 0, v167, vcc
	v_add_co_u32_e32 v152, vcc, 0x418000, v166
	global_store_short v[154:155], v147, off offset:32
	v_cvt_pk_bf16_f32 v147, v153, s0
	v_addc_co_u32_e32 v153, vcc, 0, v167, vcc
	global_store_short v[152:153], v147, off offset:32
; __device__ __forceinline__ void gemm_tile(const TileDesc& td, char* shm_c, const int wv) {
;     ...
;       int tok = td.bcol + bj * 128 + n * 16 + br_l;
;       int pos = tok & (SEQ - 1);
;       #pragma unroll
;       for (int m = 0; m < 4; ++m) {
;         int i0 = m * 16 + ar_l;
;         const float4* cs = (const float4*)(td.aux + ((long)pos * 128 + i0) * 2);
;         float4 c01 = cs[0], c23 = cs[1];
;         float cc[4] = {c01.x, c01.z, c23.x, c23.z}, ss[4] = {c01.y, c01.w, c23.y, c23.w};
;         f32x4 t1 = acc[0][bj][m][n], t2 = acc[1][bj][m][n], o1, o2;
;         #pragma unroll
;         for (int j = 0; j < 4; ++j) { o1[j] = (t1[j] * cc[j] - t2[j] * ss[j]) * sc; o2[j] = (t2[j] * cc[j] + t1[j] * ss[j]) * sc; }
;         long o = (long)tok * td.ldo + (td.brow + i0);
;         uint2 pk; pk.x = pack2(o1[0], o1[1]); pk.y = pack2(o1[2], o1[3]);
;         *(uint2*)(td.outb + o) = pk;
;         pk.x = pack2(o2[0], o2[1]); pk.y = pack2(o2[2], o2[3]);
;         *(uint2*)(td.outb + o + 128) = pk;
;         if (td.outT) {
;           u16* tp = td.outT + (long)i0 * LDT + tok;
;           #pragma unroll
;           for (int j = 0; j < 4; ++j) {
;             tp[(long)j * LDT] = (u16)(pack2(o1[j], 0.f) & 0xffffu);
;             tp[(long)(j + 128) * LDT] = (u16)(pack2(o2[j], 0.f) & 0xffffu);
;           }
.LBB0_596:
	v_add_u32_e32 v152, v143, v132
	v_mov_b32_e32 v153, v133
	v_lshl_add_u64 v[156:157], v[152:153], 3, s[40:41]
	s_nop 0
	s_and_b64 vcc, exec, s[0:1]
	s_waitcnt vmcnt(14)
	v_mov_b32_e32 v152, v212
	v_mov_b32_e32 v153, v213
	v_mov_b32_e32 v154, v214
	v_mov_b32_e32 v155, v215
	v_mov_b32_e32 v156, v216
	v_mov_b32_e32 v157, v217
	v_mov_b32_e32 v158, v218
	v_mov_b32_e32 v159, v219
	v_mov_b32_e32 v167, v154
	v_mov_b32_e32 v154, v153
	v_mov_b32_e32 v153, v158
	v_mov_b32_e32 v158, v157
	v_mov_b32_e32 v166, v152
	v_mov_b32_e32 v152, v156
	v_pk_mul_f32 v[156:157], v[112:113], v[154:155]
	v_pk_mul_f32 v[154:155], v[48:49], v[154:155]
	v_pk_mul_f32 v[168:169], v[114:115], v[158:159]
	v_pk_mul_f32 v[158:159], v[50:51], v[158:159]
	v_pk_fma_f32 v[156:157], v[48:49], v[166:167], v[156:157]
	v_pk_fma_f32 v[154:155], v[112:113], v[166:167], v[154:155] neg_lo:[0,0,1] neg_hi:[0,0,1]
	v_pk_fma_f32 v[166:167], v[50:51], v[152:153], v[168:169]
	v_pk_fma_f32 v[168:169], v[114:115], v[152:153], v[158:159] neg_lo:[0,0,1] neg_hi:[0,0,1]
	v_pk_mul_f32 v[158:159], v[134:135], v[154:155]
	v_pk_mul_f32 v[154:155], v[134:135], v[168:169]
	v_pk_mul_f32 v[156:157], v[134:135], v[156:157]
	v_pk_mul_f32 v[152:153], v[134:135], v[166:167]
	v_cvt_pk_bf16_f32 v166, v158, v159
	v_cvt_pk_bf16_f32 v167, v154, v155
	v_cvt_pk_bf16_f32 v168, v156, v157
	v_cvt_pk_bf16_f32 v169, v152, v153
	global_store_dwordx2 v[150:151], v[166:167], off offset:32
	global_store_dwordx2 v[150:151], v[168:169], off offset:288
	s_cbranch_vccnz .LBB0_598
	v_lshl_add_u64 v[166:167], v[128:129], 1, v[140:141]
	v_add_co_u32_e32 v168, vcc, 0x400000, v166
	v_cvt_pk_bf16_f32 v147, v158, s0
	s_nop 0
	v_addc_co_u32_e32 v169, vcc, 0, v167, vcc
	global_store_short v[166:167], v147, off offset:32
	v_cvt_pk_bf16_f32 v147, v156, s0
	v_add_co_u32_e32 v158, vcc, 0x8000, v166
	global_store_short v[168:169], v147, off offset:32
	v_cvt_pk_bf16_f32 v147, v159, s0
	v_addc_co_u32_e32 v159, vcc, 0, v167, vcc
	v_add_co_u32_e32 v156, vcc, 0x408000, v166
	global_store_short v[158:159], v147, off offset:32
	v_cvt_pk_bf16_f32 v147, v157, s0
	v_addc_co_u32_e32 v157, vcc, 0, v167, vcc
	global_store_short v[156:157], v147, off offset:32
	v_add_co_u32_e32 v156, vcc, s66, v166
	v_cvt_pk_bf16_f32 v147, v154, s0
	s_nop 0
	v_addc_co_u32_e32 v157, vcc, 0, v167, vcc
	global_store_short v[156:157], v147, off offset:32
	v_add_co_u32_e32 v156, vcc, 0x410000, v166
	v_cvt_pk_bf16_f32 v147, v152, s0
	s_nop 0
	v_addc_co_u32_e32 v157, vcc, 0, v167, vcc
	v_add_co_u32_e32 v154, vcc, 0x18000, v166
	global_store_short v[156:157], v147, off offset:32
	v_cvt_pk_bf16_f32 v147, v155, s0
	v_addc_co_u32_e32 v155, vcc, 0, v167, vcc
	v_add_co_u32_e32 v152, vcc, 0x418000, v166
	global_store_short v[154:155], v147, off offset:32
	v_cvt_pk_bf16_f32 v147, v153, s0
	v_addc_co_u32_e32 v153, vcc, 0, v167, vcc
	global_store_short v[152:153], v147, off offset:32
.LBB0_598:
	v_add_u32_e32 v152, v143, v142
	v_mov_b32_e32 v153, v133
	v_lshl_add_u64 v[156:157], v[152:153], 3, s[40:41]
	s_nop 0
	s_and_b64 vcc, exec, s[0:1]
	s_waitcnt vmcnt(14)
	v_mov_b32_e32 v152, v220
	v_mov_b32_e32 v153, v221
	v_mov_b32_e32 v154, v222
	v_mov_b32_e32 v155, v223
	v_mov_b32_e32 v156, v224
	v_mov_b32_e32 v157, v225
	v_mov_b32_e32 v158, v226
	v_mov_b32_e32 v159, v227
	v_mov_b32_e32 v167, v154
	v_mov_b32_e32 v154, v153
	v_mov_b32_e32 v153, v158
	v_mov_b32_e32 v158, v157
	v_mov_b32_e32 v166, v152
	v_mov_b32_e32 v152, v156
	v_pk_mul_f32 v[156:157], v[104:105], v[154:155]
	v_pk_mul_f32 v[154:155], v[40:41], v[154:155]
	v_pk_mul_f32 v[168:169], v[106:107], v[158:159]
	v_pk_mul_f32 v[158:159], v[42:43], v[158:159]
	v_pk_fma_f32 v[156:157], v[40:41], v[166:167], v[156:157]
	v_pk_fma_f32 v[154:155], v[104:105], v[166:167], v[154:155] neg_lo:[0,0,1] neg_hi:[0,0,1]
	v_pk_fma_f32 v[166:167], v[42:43], v[152:153], v[168:169]
	v_pk_fma_f32 v[168:169], v[106:107], v[152:153], v[158:159] neg_lo:[0,0,1] neg_hi:[0,0,1]
	v_pk_mul_f32 v[158:159], v[134:135], v[154:155]
	v_pk_mul_f32 v[154:155], v[134:135], v[168:169]
	v_pk_mul_f32 v[156:157], v[134:135], v[156:157]
	v_pk_mul_f32 v[152:153], v[134:135], v[166:167]
	v_cvt_pk_bf16_f32 v166, v158, v159
	v_cvt_pk_bf16_f32 v167, v154, v155
	v_cvt_pk_bf16_f32 v168, v156, v157
	v_cvt_pk_bf16_f32 v169, v152, v153
	global_store_dwordx2 v[150:151], v[166:167], off offset:64
	global_store_dwordx2 v[150:151], v[168:169], off offset:320
	s_cbranch_vccnz .LBB0_600
	v_lshl_add_u64 v[166:167], v[128:129], 1, v[144:145]
	v_add_co_u32_e32 v168, vcc, 0x400000, v166
	v_cvt_pk_bf16_f32 v147, v158, s0
	s_nop 0
	v_addc_co_u32_e32 v169, vcc, 0, v167, vcc
	global_store_short v[166:167], v147, off offset:32
	v_cvt_pk_bf16_f32 v147, v156, s0
	v_add_co_u32_e32 v158, vcc, 0x8000, v166
	global_store_short v[168:169], v147, off offset:32
	v_cvt_pk_bf16_f32 v147, v159, s0
	v_addc_co_u32_e32 v159, vcc, 0, v167, vcc
	v_add_co_u32_e32 v156, vcc, 0x408000, v166
	global_store_short v[158:159], v147, off offset:32
	v_cvt_pk_bf16_f32 v147, v157, s0
	v_addc_co_u32_e32 v157, vcc, 0, v167, vcc
	global_store_short v[156:157], v147, off offset:32
	v_add_co_u32_e32 v156, vcc, s66, v166
	v_cvt_pk_bf16_f32 v147, v154, s0
	s_nop 0
	v_addc_co_u32_e32 v157, vcc, 0, v167, vcc
	global_store_short v[156:157], v147, off offset:32
	v_add_co_u32_e32 v156, vcc, 0x410000, v166
	v_cvt_pk_bf16_f32 v147, v152, s0
	s_nop 0
	v_addc_co_u32_e32 v157, vcc, 0, v167, vcc
	v_add_co_u32_e32 v154, vcc, 0x18000, v166
	global_store_short v[156:157], v147, off offset:32
	v_cvt_pk_bf16_f32 v147, v155, s0
	v_addc_co_u32_e32 v155, vcc, 0, v167, vcc
	v_add_co_u32_e32 v152, vcc, 0x418000, v166
	global_store_short v[154:155], v147, off offset:32
	v_cvt_pk_bf16_f32 v147, v153, s0
	v_addc_co_u32_e32 v153, vcc, 0, v167, vcc
	global_store_short v[152:153], v147, off offset:32
; __device__ __forceinline__ void gemm_tile(const TileDesc& td, char* shm_c, const int wv) {
;     ...
;       int tok = td.bcol + bj * 128 + n * 16 + br_l;
;       int pos = tok & (SEQ - 1);
;       #pragma unroll
;       for (int m = 0; m < 4; ++m) {
;         int i0 = m * 16 + ar_l;
;         const float4* cs = (const float4*)(td.aux + ((long)pos * 128 + i0) * 2);
;         float4 c01 = cs[0], c23 = cs[1];
;         float cc[4] = {c01.x, c01.z, c23.x, c23.z}, ss[4] = {c01.y, c01.w, c23.y, c23.w};
;         f32x4 t1 = acc[0][bj][m][n], t2 = acc[1][bj][m][n], o1, o2;
;         #pragma unroll
;         for (int j = 0; j < 4; ++j) { o1[j] = (t1[j] * cc[j] - t2[j] * ss[j]) * sc; o2[j] = (t2[j] * cc[j] + t1[j] * ss[j]) * sc; }
;         long o = (long)tok * td.ldo + (td.brow + i0);
;         uint2 pk; pk.x = pack2(o1[0], o1[1]); pk.y = pack2(o1[2], o1[3]);
;         *(uint2*)(td.outb + o) = pk;
;         pk.x = pack2(o2[0], o2[1]); pk.y = pack2(o2[2], o2[3]);
;         *(uint2*)(td.outb + o + 128) = pk;
;         if (td.outT) {
;           u16* tp = td.outT + (long)i0 * LDT + tok;
;           #pragma unroll
;           for (int j = 0; j < 4; ++j) {
;             tp[(long)j * LDT] = (u16)(pack2(o1[j], 0.f) & 0xffffu);
;             tp[(long)(j + 128) * LDT] = (u16)(pack2(o2[j], 0.f) & 0xffffu);
;           }
.LBB0_600:
	v_add_u32_e32 v152, v143, v146
	v_mov_b32_e32 v153, v133
	v_lshl_add_u64 v[156:157], v[152:153], 3, s[40:41]
	s_nop 0
	s_and_b64 vcc, exec, s[0:1]
	s_waitcnt vmcnt(14)
	v_mov_b32_e32 v152, v228
	v_mov_b32_e32 v153, v229
	v_mov_b32_e32 v154, v230
	v_mov_b32_e32 v155, v231
	v_mov_b32_e32 v156, v232
	v_mov_b32_e32 v157, v233
	v_mov_b32_e32 v158, v234
	v_mov_b32_e32 v159, v235
	v_mov_b32_e32 v167, v154
	v_mov_b32_e32 v154, v153
	v_mov_b32_e32 v153, v158
	v_mov_b32_e32 v158, v157
	v_mov_b32_e32 v166, v152
	v_mov_b32_e32 v152, v156
	v_pk_mul_f32 v[156:157], v[96:97], v[154:155]
	v_pk_mul_f32 v[154:155], v[32:33], v[154:155]
	v_pk_mul_f32 v[168:169], v[98:99], v[158:159]
	v_pk_mul_f32 v[158:159], v[34:35], v[158:159]
	v_pk_fma_f32 v[156:157], v[32:33], v[166:167], v[156:157]
	v_pk_fma_f32 v[154:155], v[96:97], v[166:167], v[154:155] neg_lo:[0,0,1] neg_hi:[0,0,1]
	v_pk_fma_f32 v[166:167], v[34:35], v[152:153], v[168:169]
	v_pk_fma_f32 v[168:169], v[98:99], v[152:153], v[158:159] neg_lo:[0,0,1] neg_hi:[0,0,1]
	v_pk_mul_f32 v[158:159], v[134:135], v[154:155]
	v_pk_mul_f32 v[154:155], v[134:135], v[168:169]
	v_pk_mul_f32 v[156:157], v[134:135], v[156:157]
	v_pk_mul_f32 v[152:153], v[134:135], v[166:167]
	v_cvt_pk_bf16_f32 v166, v158, v159
	v_cvt_pk_bf16_f32 v167, v154, v155
	v_cvt_pk_bf16_f32 v168, v156, v157
	v_cvt_pk_bf16_f32 v169, v152, v153
	global_store_dwordx2 v[150:151], v[166:167], off offset:96
	global_store_dwordx2 v[150:151], v[168:169], off offset:352
	s_cbranch_vccnz .LBB0_602
	v_lshl_add_u64 v[150:151], v[128:129], 1, v[148:149]
	v_add_co_u32_e32 v166, vcc, 0x400000, v150
	v_cvt_pk_bf16_f32 v143, v158, s0
	s_nop 0
	v_addc_co_u32_e32 v167, vcc, 0, v151, vcc
	global_store_short v[150:151], v143, off offset:32
	v_cvt_pk_bf16_f32 v143, v156, s0
	v_add_co_u32_e32 v158, vcc, 0x8000, v150
	global_store_short v[166:167], v143, off offset:32
	v_cvt_pk_bf16_f32 v143, v159, s0
	v_addc_co_u32_e32 v159, vcc, 0, v151, vcc
	v_add_co_u32_e32 v156, vcc, 0x408000, v150
	global_store_short v[158:159], v143, off offset:32
	v_cvt_pk_bf16_f32 v143, v157, s0
	v_addc_co_u32_e32 v157, vcc, 0, v151, vcc
	global_store_short v[156:157], v143, off offset:32
	v_add_co_u32_e32 v156, vcc, s66, v150
	v_cvt_pk_bf16_f32 v143, v154, s0
	s_nop 0
	v_addc_co_u32_e32 v157, vcc, 0, v151, vcc
	global_store_short v[156:157], v143, off offset:32
	v_add_co_u32_e32 v156, vcc, 0x410000, v150
	v_cvt_pk_bf16_f32 v143, v152, s0
	s_nop 0
	v_addc_co_u32_e32 v157, vcc, 0, v151, vcc
	v_add_co_u32_e32 v154, vcc, 0x18000, v150
	global_store_short v[156:157], v143, off offset:32
	v_cvt_pk_bf16_f32 v143, v155, s0
	v_addc_co_u32_e32 v155, vcc, 0, v151, vcc
	v_add_co_u32_e32 v150, vcc, 0x418000, v150
	global_store_short v[154:155], v143, off offset:32
	v_cvt_pk_bf16_f32 v143, v153, s0
	v_addc_co_u32_e32 v151, vcc, 0, v151, vcc
	global_store_short v[150:151], v143, off offset:32
.LBB0_602:
	global_load_dwordx4 v[172:175], v[240:241], off
	global_load_dwordx4 v[176:179], v[240:241], off offset:16
	global_load_dwordx4 v[180:183], v[240:241], off offset:128
	global_load_dwordx4 v[184:187], v[240:241], off offset:144
	global_load_dwordx4 v[188:191], v[240:241], off offset:256
	global_load_dwordx4 v[192:195], v[240:241], off offset:272
	global_load_dwordx4 v[196:199], v[240:241], off offset:384
	global_load_dwordx4 v[200:203], v[240:241], off offset:400
	global_load_dwordx4 v[204:207], v[242:243], off
	global_load_dwordx4 v[208:211], v[242:243], off offset:16
	global_load_dwordx4 v[212:215], v[242:243], off offset:128
	global_load_dwordx4 v[216:219], v[242:243], off offset:144
	global_load_dwordx4 v[220:223], v[242:243], off offset:256
	global_load_dwordx4 v[224:227], v[242:243], off offset:272
	global_load_dwordx4 v[228:231], v[242:243], off offset:384
	global_load_dwordx4 v[232:235], v[242:243], off offset:400
	v_or_b32_e32 v147, 0x80, v128
	v_lshlrev_b32_e32 v143, 7, v147
	v_and_b32_e32 v143, 0x7f780, v143
	v_add_u32_e32 v150, v143, v136
	v_mov_b32_e32 v151, v133
	v_lshl_add_u64 v[150:151], v[150:151], 3, s[40:41]
	v_mul_lo_u32 v165, s35, v147
	v_mad_u64_u32 v[150:151], s[2:3], s34, v147, 0
	v_add3_u32 v151, v151, v137, v165
	v_lshl_add_u64 v[150:151], v[150:151], 1, s[36:37]
	s_and_b64 vcc, exec, s[0:1]
	v_lshl_add_u64 v[150:151], v[130:131], 1, v[150:151]
	s_waitcnt vmcnt(14)
	v_mov_b32_e32 v152, v172
	v_mov_b32_e32 v153, v173
	v_mov_b32_e32 v154, v174
	v_mov_b32_e32 v155, v175
	v_mov_b32_e32 v156, v176
	v_mov_b32_e32 v157, v177
	v_mov_b32_e32 v158, v178
	v_mov_b32_e32 v159, v179
	v_mov_b32_e32 v167, v154
	v_mov_b32_e32 v154, v153
	v_mov_b32_e32 v153, v158
	v_mov_b32_e32 v158, v157
	v_mov_b32_e32 v166, v152
	v_mov_b32_e32 v152, v156
	v_pk_mul_f32 v[156:157], v[92:93], v[154:155]
	v_pk_mul_f32 v[154:155], v[28:29], v[154:155]
	v_pk_mul_f32 v[168:169], v[94:95], v[158:159]
	v_pk_mul_f32 v[158:159], v[30:31], v[158:159]
	v_pk_fma_f32 v[156:157], v[28:29], v[166:167], v[156:157]
	v_pk_fma_f32 v[154:155], v[92:93], v[166:167], v[154:155] neg_lo:[0,0,1] neg_hi:[0,0,1]
	v_pk_fma_f32 v[166:167], v[30:31], v[152:153], v[168:169]
	v_pk_fma_f32 v[168:169], v[94:95], v[152:153], v[158:159] neg_lo:[0,0,1] neg_hi:[0,0,1]
	v_pk_mul_f32 v[158:159], v[134:135], v[154:155]
	v_pk_mul_f32 v[154:155], v[134:135], v[168:169]
	v_pk_mul_f32 v[156:157], v[134:135], v[156:157]
	v_pk_mul_f32 v[152:153], v[134:135], v[166:167]
	v_cvt_pk_bf16_f32 v166, v158, v159
	v_cvt_pk_bf16_f32 v167, v154, v155
	v_cvt_pk_bf16_f32 v168, v156, v157
	v_cvt_pk_bf16_f32 v169, v152, v153
	global_store_dwordx2 v[150:151], v[166:167], off
	global_store_dwordx2 v[150:151], v[168:169], off offset:256
	s_cbranch_vccnz .LBB0_604
	v_lshl_add_u64 v[166:167], v[128:129], 1, v[138:139]
	v_add_co_u32_e32 v168, vcc, 0x400000, v166
	v_cvt_pk_bf16_f32 v147, v158, s0
	s_nop 0
	v_addc_co_u32_e32 v169, vcc, 0, v167, vcc
	global_store_short v[166:167], v147, off offset:256
	v_cvt_pk_bf16_f32 v147, v156, s0
	v_add_co_u32_e32 v158, vcc, 0x8000, v166
	global_store_short v[168:169], v147, off offset:256
	v_cvt_pk_bf16_f32 v147, v159, s0
	v_addc_co_u32_e32 v159, vcc, 0, v167, vcc
	v_add_co_u32_e32 v156, vcc, 0x408000, v166
	global_store_short v[158:159], v147, off offset:256
	v_cvt_pk_bf16_f32 v147, v157, s0
	v_addc_co_u32_e32 v157, vcc, 0, v167, vcc
	global_store_short v[156:157], v147, off offset:256
	v_add_co_u32_e32 v156, vcc, s66, v166
	v_cvt_pk_bf16_f32 v147, v154, s0
	s_nop 0
	v_addc_co_u32_e32 v157, vcc, 0, v167, vcc
	global_store_short v[156:157], v147, off offset:256
	v_add_co_u32_e32 v156, vcc, 0x410000, v166
	v_cvt_pk_bf16_f32 v147, v152, s0
	s_nop 0
	v_addc_co_u32_e32 v157, vcc, 0, v167, vcc
	v_add_co_u32_e32 v154, vcc, 0x18000, v166
	global_store_short v[156:157], v147, off offset:256
	v_cvt_pk_bf16_f32 v147, v155, s0
	v_addc_co_u32_e32 v155, vcc, 0, v167, vcc
	v_add_co_u32_e32 v152, vcc, 0x418000, v166
	global_store_short v[154:155], v147, off offset:256
	v_cvt_pk_bf16_f32 v147, v153, s0
	v_addc_co_u32_e32 v153, vcc, 0, v167, vcc
	global_store_short v[152:153], v147, off offset:256
; __device__ __forceinline__ void gemm_tile(const TileDesc& td, char* shm_c, const int wv) {
;     ...
;       int tok = td.bcol + bj * 128 + n * 16 + br_l;
;       int pos = tok & (SEQ - 1);
;       #pragma unroll
;       for (int m = 0; m < 4; ++m) {
;         int i0 = m * 16 + ar_l;
;         const float4* cs = (const float4*)(td.aux + ((long)pos * 128 + i0) * 2);
;         float4 c01 = cs[0], c23 = cs[1];
;         float cc[4] = {c01.x, c01.z, c23.x, c23.z}, ss[4] = {c01.y, c01.w, c23.y, c23.w};
;         f32x4 t1 = acc[0][bj][m][n], t2 = acc[1][bj][m][n], o1, o2;
;         #pragma unroll
;         for (int j = 0; j < 4; ++j) { o1[j] = (t1[j] * cc[j] - t2[j] * ss[j]) * sc; o2[j] = (t2[j] * cc[j] + t1[j] * ss[j]) * sc; }
;         long o = (long)tok * td.ldo + (td.brow + i0);
;         uint2 pk; pk.x = pack2(o1[0], o1[1]); pk.y = pack2(o1[2], o1[3]);
;         *(uint2*)(td.outb + o) = pk;
;         pk.x = pack2(o2[0], o2[1]); pk.y = pack2(o2[2], o2[3]);
;         *(uint2*)(td.outb + o + 128) = pk;
;         if (td.outT) {
;           u16* tp = td.outT + (long)i0 * LDT + tok;
;           #pragma unroll
;           for (int j = 0; j < 4; ++j) {
;             tp[(long)j * LDT] = (u16)(pack2(o1[j], 0.f) & 0xffffu);
;             tp[(long)(j + 128) * LDT] = (u16)(pack2(o2[j], 0.f) & 0xffffu);
;           }
.LBB0_604:
	v_add_u32_e32 v152, v143, v132
	v_mov_b32_e32 v153, v133
	v_lshl_add_u64 v[156:157], v[152:153], 3, s[40:41]
	s_nop 0
	s_and_b64 vcc, exec, s[0:1]
	s_waitcnt vmcnt(14)
	v_mov_b32_e32 v152, v180
	v_mov_b32_e32 v153, v181
	v_mov_b32_e32 v154, v182
	v_mov_b32_e32 v155, v183
	v_mov_b32_e32 v156, v184
	v_mov_b32_e32 v157, v185
	v_mov_b32_e32 v158, v186
	v_mov_b32_e32 v159, v187
	v_mov_b32_e32 v167, v154
	v_mov_b32_e32 v154, v153
	v_mov_b32_e32 v153, v158
	v_mov_b32_e32 v158, v157
	v_mov_b32_e32 v166, v152
	v_mov_b32_e32 v152, v156
	v_pk_mul_f32 v[156:157], v[84:85], v[154:155]
	v_pk_mul_f32 v[154:155], v[20:21], v[154:155]
	v_pk_mul_f32 v[168:169], v[86:87], v[158:159]
	v_pk_mul_f32 v[158:159], v[22:23], v[158:159]
	v_pk_fma_f32 v[156:157], v[20:21], v[166:167], v[156:157]
	v_pk_fma_f32 v[154:155], v[84:85], v[166:167], v[154:155] neg_lo:[0,0,1] neg_hi:[0,0,1]
	v_pk_fma_f32 v[166:167], v[22:23], v[152:153], v[168:169]
	v_pk_fma_f32 v[168:169], v[86:87], v[152:153], v[158:159] neg_lo:[0,0,1] neg_hi:[0,0,1]
	v_pk_mul_f32 v[158:159], v[134:135], v[154:155]
	v_pk_mul_f32 v[154:155], v[134:135], v[168:169]
	v_pk_mul_f32 v[156:157], v[134:135], v[156:157]
	v_pk_mul_f32 v[152:153], v[134:135], v[166:167]
	v_cvt_pk_bf16_f32 v166, v158, v159
	v_cvt_pk_bf16_f32 v167, v154, v155
	v_cvt_pk_bf16_f32 v168, v156, v157
	v_cvt_pk_bf16_f32 v169, v152, v153
	global_store_dwordx2 v[150:151], v[166:167], off offset:32
	global_store_dwordx2 v[150:151], v[168:169], off offset:288
	s_cbranch_vccnz .LBB0_606
	v_lshl_add_u64 v[166:167], v[128:129], 1, v[140:141]
	v_add_co_u32_e32 v168, vcc, 0x400000, v166
	v_cvt_pk_bf16_f32 v147, v158, s0
	s_nop 0
	v_addc_co_u32_e32 v169, vcc, 0, v167, vcc
	global_store_short v[166:167], v147, off offset:256
	v_cvt_pk_bf16_f32 v147, v156, s0
	v_add_co_u32_e32 v158, vcc, 0x8000, v166
	global_store_short v[168:169], v147, off offset:256
	v_cvt_pk_bf16_f32 v147, v159, s0
	v_addc_co_u32_e32 v159, vcc, 0, v167, vcc
	v_add_co_u32_e32 v156, vcc, 0x408000, v166
	global_store_short v[158:159], v147, off offset:256
	v_cvt_pk_bf16_f32 v147, v157, s0
	v_addc_co_u32_e32 v157, vcc, 0, v167, vcc
	global_store_short v[156:157], v147, off offset:256
	v_add_co_u32_e32 v156, vcc, s66, v166
	v_cvt_pk_bf16_f32 v147, v154, s0
	s_nop 0
	v_addc_co_u32_e32 v157, vcc, 0, v167, vcc
	global_store_short v[156:157], v147, off offset:256
	v_add_co_u32_e32 v156, vcc, 0x410000, v166
	v_cvt_pk_bf16_f32 v147, v152, s0
	s_nop 0
	v_addc_co_u32_e32 v157, vcc, 0, v167, vcc
	v_add_co_u32_e32 v154, vcc, 0x18000, v166
	global_store_short v[156:157], v147, off offset:256
	v_cvt_pk_bf16_f32 v147, v155, s0
	v_addc_co_u32_e32 v155, vcc, 0, v167, vcc
	v_add_co_u32_e32 v152, vcc, 0x418000, v166
	global_store_short v[154:155], v147, off offset:256
	v_cvt_pk_bf16_f32 v147, v153, s0
	v_addc_co_u32_e32 v153, vcc, 0, v167, vcc
	global_store_short v[152:153], v147, off offset:256
.LBB0_606:
	v_add_u32_e32 v152, v143, v142
	v_mov_b32_e32 v153, v133
	v_lshl_add_u64 v[156:157], v[152:153], 3, s[40:41]
	s_nop 0
	s_and_b64 vcc, exec, s[0:1]
	s_waitcnt vmcnt(14)
	v_mov_b32_e32 v152, v188
	v_mov_b32_e32 v153, v189
	v_mov_b32_e32 v154, v190
	v_mov_b32_e32 v155, v191
	v_mov_b32_e32 v156, v192
	v_mov_b32_e32 v157, v193
	v_mov_b32_e32 v158, v194
	v_mov_b32_e32 v159, v195
	v_mov_b32_e32 v167, v154
	v_mov_b32_e32 v154, v153
	v_mov_b32_e32 v153, v158
	v_mov_b32_e32 v158, v157
	v_mov_b32_e32 v166, v152
	v_mov_b32_e32 v152, v156
	v_pk_mul_f32 v[156:157], v[76:77], v[154:155]
	v_pk_mul_f32 v[154:155], v[12:13], v[154:155]
	v_pk_mul_f32 v[168:169], v[78:79], v[158:159]
	v_pk_mul_f32 v[158:159], v[14:15], v[158:159]
	v_pk_fma_f32 v[156:157], v[12:13], v[166:167], v[156:157]
	v_pk_fma_f32 v[154:155], v[76:77], v[166:167], v[154:155] neg_lo:[0,0,1] neg_hi:[0,0,1]
	v_pk_fma_f32 v[166:167], v[14:15], v[152:153], v[168:169]
	v_pk_fma_f32 v[168:169], v[78:79], v[152:153], v[158:159] neg_lo:[0,0,1] neg_hi:[0,0,1]
	v_pk_mul_f32 v[158:159], v[134:135], v[154:155]
	v_pk_mul_f32 v[154:155], v[134:135], v[168:169]
	v_pk_mul_f32 v[156:157], v[134:135], v[156:157]
	v_pk_mul_f32 v[152:153], v[134:135], v[166:167]
	v_cvt_pk_bf16_f32 v166, v158, v159
	v_cvt_pk_bf16_f32 v167, v154, v155
	v_cvt_pk_bf16_f32 v168, v156, v157
	v_cvt_pk_bf16_f32 v169, v152, v153
	global_store_dwordx2 v[150:151], v[166:167], off offset:64
	global_store_dwordx2 v[150:151], v[168:169], off offset:320
	s_cbranch_vccnz .LBB0_608
	v_lshl_add_u64 v[166:167], v[128:129], 1, v[144:145]
	v_add_co_u32_e32 v168, vcc, 0x400000, v166
	v_cvt_pk_bf16_f32 v147, v158, s0
	s_nop 0
	v_addc_co_u32_e32 v169, vcc, 0, v167, vcc
	global_store_short v[166:167], v147, off offset:256
	v_cvt_pk_bf16_f32 v147, v156, s0
	v_add_co_u32_e32 v158, vcc, 0x8000, v166
	global_store_short v[168:169], v147, off offset:256
	v_cvt_pk_bf16_f32 v147, v159, s0
	v_addc_co_u32_e32 v159, vcc, 0, v167, vcc
	v_add_co_u32_e32 v156, vcc, 0x408000, v166
	global_store_short v[158:159], v147, off offset:256
	v_cvt_pk_bf16_f32 v147, v157, s0
	v_addc_co_u32_e32 v157, vcc, 0, v167, vcc
	global_store_short v[156:157], v147, off offset:256
	v_add_co_u32_e32 v156, vcc, s66, v166
	v_cvt_pk_bf16_f32 v147, v154, s0
	s_nop 0
	v_addc_co_u32_e32 v157, vcc, 0, v167, vcc
	global_store_short v[156:157], v147, off offset:256
	v_add_co_u32_e32 v156, vcc, 0x410000, v166
	v_cvt_pk_bf16_f32 v147, v152, s0
	s_nop 0
	v_addc_co_u32_e32 v157, vcc, 0, v167, vcc
	v_add_co_u32_e32 v154, vcc, 0x18000, v166
	global_store_short v[156:157], v147, off offset:256
	v_cvt_pk_bf16_f32 v147, v155, s0
	v_addc_co_u32_e32 v155, vcc, 0, v167, vcc
	v_add_co_u32_e32 v152, vcc, 0x418000, v166
	global_store_short v[154:155], v147, off offset:256
	v_cvt_pk_bf16_f32 v147, v153, s0
	v_addc_co_u32_e32 v153, vcc, 0, v167, vcc
	global_store_short v[152:153], v147, off offset:256
; __device__ __forceinline__ void gemm_tile(const TileDesc& td, char* shm_c, const int wv) {
;     ...
;       int tok = td.bcol + bj * 128 + n * 16 + br_l;
;       int pos = tok & (SEQ - 1);
;       #pragma unroll
;       for (int m = 0; m < 4; ++m) {
;         int i0 = m * 16 + ar_l;
;         const float4* cs = (const float4*)(td.aux + ((long)pos * 128 + i0) * 2);
;         float4 c01 = cs[0], c23 = cs[1];
;         float cc[4] = {c01.x, c01.z, c23.x, c23.z}, ss[4] = {c01.y, c01.w, c23.y, c23.w};
;         f32x4 t1 = acc[0][bj][m][n], t2 = acc[1][bj][m][n], o1, o2;
;         #pragma unroll
;         for (int j = 0; j < 4; ++j) { o1[j] = (t1[j] * cc[j] - t2[j] * ss[j]) * sc; o2[j] = (t2[j] * cc[j] + t1[j] * ss[j]) * sc; }
;         long o = (long)tok * td.ldo + (td.brow + i0);
;         uint2 pk; pk.x = pack2(o1[0], o1[1]); pk.y = pack2(o1[2], o1[3]);
;         *(uint2*)(td.outb + o) = pk;
;         pk.x = pack2(o2[0], o2[1]); pk.y = pack2(o2[2], o2[3]);
;         *(uint2*)(td.outb + o + 128) = pk;
;         if (td.outT) {
;           u16* tp = td.outT + (long)i0 * LDT + tok;
;           #pragma unroll
;           for (int j = 0; j < 4; ++j) {
;             tp[(long)j * LDT] = (u16)(pack2(o1[j], 0.f) & 0xffffu);
;             tp[(long)(j + 128) * LDT] = (u16)(pack2(o2[j], 0.f) & 0xffffu);
;           }
.LBB0_608:
	v_add_u32_e32 v152, v143, v146
	v_mov_b32_e32 v153, v133
	v_lshl_add_u64 v[156:157], v[152:153], 3, s[40:41]
	s_nop 0
	s_and_b64 vcc, exec, s[0:1]
	s_waitcnt vmcnt(14)
	v_mov_b32_e32 v152, v196
	v_mov_b32_e32 v153, v197
	v_mov_b32_e32 v154, v198
	v_mov_b32_e32 v155, v199
	v_mov_b32_e32 v156, v200
	v_mov_b32_e32 v157, v201
	v_mov_b32_e32 v158, v202
	v_mov_b32_e32 v159, v203
	v_mov_b32_e32 v167, v154
	v_mov_b32_e32 v154, v153
	v_mov_b32_e32 v153, v158
	v_mov_b32_e32 v158, v157
	v_mov_b32_e32 v166, v152
	v_mov_b32_e32 v152, v156
	v_pk_mul_f32 v[156:157], v[68:69], v[154:155]
	v_pk_mul_f32 v[154:155], v[4:5], v[154:155]
	v_pk_mul_f32 v[168:169], v[70:71], v[158:159]
	v_pk_mul_f32 v[158:159], v[6:7], v[158:159]
	v_pk_fma_f32 v[156:157], v[4:5], v[166:167], v[156:157]
	v_pk_fma_f32 v[154:155], v[68:69], v[166:167], v[154:155] neg_lo:[0,0,1] neg_hi:[0,0,1]
	v_pk_fma_f32 v[166:167], v[6:7], v[152:153], v[168:169]
	v_pk_fma_f32 v[168:169], v[70:71], v[152:153], v[158:159] neg_lo:[0,0,1] neg_hi:[0,0,1]
	v_pk_mul_f32 v[158:159], v[134:135], v[154:155]
	v_pk_mul_f32 v[154:155], v[134:135], v[168:169]
	v_pk_mul_f32 v[156:157], v[134:135], v[156:157]
	v_pk_mul_f32 v[152:153], v[134:135], v[166:167]
	v_cvt_pk_bf16_f32 v166, v158, v159
	v_cvt_pk_bf16_f32 v167, v154, v155
	v_cvt_pk_bf16_f32 v168, v156, v157
	v_cvt_pk_bf16_f32 v169, v152, v153
	global_store_dwordx2 v[150:151], v[166:167], off offset:96
	global_store_dwordx2 v[150:151], v[168:169], off offset:352
	s_cbranch_vccnz .LBB0_610
	v_lshl_add_u64 v[150:151], v[128:129], 1, v[148:149]
	v_add_co_u32_e32 v166, vcc, 0x400000, v150
	v_cvt_pk_bf16_f32 v143, v158, s0
	s_nop 0
	v_addc_co_u32_e32 v167, vcc, 0, v151, vcc
	global_store_short v[150:151], v143, off offset:256
	v_cvt_pk_bf16_f32 v143, v156, s0
	v_add_co_u32_e32 v158, vcc, 0x8000, v150
	global_store_short v[166:167], v143, off offset:256
	v_cvt_pk_bf16_f32 v143, v159, s0
	v_addc_co_u32_e32 v159, vcc, 0, v151, vcc
	v_add_co_u32_e32 v156, vcc, 0x408000, v150
	global_store_short v[158:159], v143, off offset:256
	v_cvt_pk_bf16_f32 v143, v157, s0
	v_addc_co_u32_e32 v157, vcc, 0, v151, vcc
	global_store_short v[156:157], v143, off offset:256
	v_add_co_u32_e32 v156, vcc, s66, v150
	v_cvt_pk_bf16_f32 v143, v154, s0
	s_nop 0
	v_addc_co_u32_e32 v157, vcc, 0, v151, vcc
	global_store_short v[156:157], v143, off offset:256
	v_add_co_u32_e32 v156, vcc, 0x410000, v150
	v_cvt_pk_bf16_f32 v143, v152, s0
	s_nop 0
	v_addc_co_u32_e32 v157, vcc, 0, v151, vcc
	v_add_co_u32_e32 v154, vcc, 0x18000, v150
	global_store_short v[156:157], v143, off offset:256
	v_cvt_pk_bf16_f32 v143, v155, s0
	v_addc_co_u32_e32 v155, vcc, 0, v151, vcc
	v_add_co_u32_e32 v150, vcc, 0x418000, v150
	global_store_short v[154:155], v143, off offset:256
	v_cvt_pk_bf16_f32 v143, v153, s0
	v_addc_co_u32_e32 v151, vcc, 0, v151, vcc
	global_store_short v[150:151], v143, off offset:256
.LBB0_610:
	v_or_b32_e32 v143, 0x90, v128
	v_lshlrev_b32_e32 v147, 7, v143
	v_and_b32_e32 v147, 0x7ff80, v147
	v_add_u32_e32 v150, v147, v136
	v_mov_b32_e32 v151, v133
	v_lshl_add_u64 v[154:155], v[150:151], 3, s[40:41]
	s_nop 0
	v_mul_lo_u32 v165, s35, v143
	v_mad_u64_u32 v[158:159], s[2:3], s34, v143, 0
	v_add3_u32 v159, v159, v137, v165
	v_lshl_add_u64 v[158:159], v[158:159], 1, s[36:37]
	v_lshl_add_u64 v[130:131], v[130:131], 1, v[158:159]
	s_and_b64 vcc, exec, s[0:1]
	s_waitcnt vmcnt(14)
	v_mov_b32_e32 v150, v204
	v_mov_b32_e32 v151, v205
	v_mov_b32_e32 v152, v206
	v_mov_b32_e32 v153, v207
	v_mov_b32_e32 v154, v208
	v_mov_b32_e32 v155, v209
	v_mov_b32_e32 v156, v210
	v_mov_b32_e32 v157, v211
	v_mov_b32_e32 v159, v152
	v_mov_b32_e32 v152, v151
	v_mov_b32_e32 v151, v156
	v_mov_b32_e32 v156, v155
	v_mov_b32_e32 v158, v150
	v_mov_b32_e32 v150, v154
	v_pk_mul_f32 v[154:155], v[88:89], v[152:153]
	v_pk_mul_f32 v[152:153], v[24:25], v[152:153]
	v_pk_mul_f32 v[166:167], v[90:91], v[156:157]
	v_pk_mul_f32 v[156:157], v[26:27], v[156:157]
	v_pk_fma_f32 v[154:155], v[24:25], v[158:159], v[154:155]
	v_pk_fma_f32 v[152:153], v[88:89], v[158:159], v[152:153] neg_lo:[0,0,1] neg_hi:[0,0,1]
	v_pk_fma_f32 v[158:159], v[26:27], v[150:151], v[166:167]
	v_pk_fma_f32 v[166:167], v[90:91], v[150:151], v[156:157] neg_lo:[0,0,1] neg_hi:[0,0,1]
	v_pk_mul_f32 v[156:157], v[134:135], v[152:153]
	v_pk_mul_f32 v[152:153], v[134:135], v[166:167]
	v_pk_mul_f32 v[154:155], v[134:135], v[154:155]
	v_pk_mul_f32 v[150:151], v[134:135], v[158:159]
	v_cvt_pk_bf16_f32 v158, v156, v157
	v_cvt_pk_bf16_f32 v159, v152, v153
	v_cvt_pk_bf16_f32 v166, v154, v155
	v_cvt_pk_bf16_f32 v167, v150, v151
	global_store_dwordx2 v[130:131], v[158:159], off
	global_store_dwordx2 v[130:131], v[166:167], off offset:256
	s_cbranch_vccnz .LBB0_612
	v_lshl_add_u64 v[138:139], v[128:129], 1, v[138:139]
	v_add_co_u32_e32 v158, vcc, 0x400000, v138
	v_cvt_pk_bf16_f32 v137, v156, s0
	s_nop 0
	v_addc_co_u32_e32 v159, vcc, 0, v139, vcc
	global_store_short v[138:139], v137, off offset:288
	v_cvt_pk_bf16_f32 v137, v154, s0
	v_add_co_u32_e32 v156, vcc, 0x8000, v138
	global_store_short v[158:159], v137, off offset:288
	v_cvt_pk_bf16_f32 v137, v157, s0
	v_addc_co_u32_e32 v157, vcc, 0, v139, vcc
	v_add_co_u32_e32 v154, vcc, 0x408000, v138
	global_store_short v[156:157], v137, off offset:288
	v_cvt_pk_bf16_f32 v137, v155, s0
	v_addc_co_u32_e32 v155, vcc, 0, v139, vcc
	global_store_short v[154:155], v137, off offset:288
	v_add_co_u32_e32 v154, vcc, s66, v138
	v_cvt_pk_bf16_f32 v137, v152, s0
	s_nop 0
	v_addc_co_u32_e32 v155, vcc, 0, v139, vcc
	global_store_short v[154:155], v137, off offset:288
	v_add_co_u32_e32 v154, vcc, 0x410000, v138
	v_cvt_pk_bf16_f32 v137, v150, s0
	s_nop 0
	v_addc_co_u32_e32 v155, vcc, 0, v139, vcc
	v_add_co_u32_e32 v152, vcc, 0x18000, v138
	global_store_short v[154:155], v137, off offset:288
	v_cvt_pk_bf16_f32 v137, v153, s0
	v_addc_co_u32_e32 v153, vcc, 0, v139, vcc
	v_add_co_u32_e32 v138, vcc, 0x418000, v138
	global_store_short v[152:153], v137, off offset:288
	v_cvt_pk_bf16_f32 v137, v151, s0
	v_addc_co_u32_e32 v139, vcc, 0, v139, vcc
	global_store_short v[138:139], v137, off offset:288
; __device__ __forceinline__ void gemm_tile(const TileDesc& td, char* shm_c, const int wv) {
;     ...
;       int tok = td.bcol + bj * 128 + n * 16 + br_l;
;       int pos = tok & (SEQ - 1);
;       #pragma unroll
;       for (int m = 0; m < 4; ++m) {
;         int i0 = m * 16 + ar_l;
;         const float4* cs = (const float4*)(td.aux + ((long)pos * 128 + i0) * 2);
;         float4 c01 = cs[0], c23 = cs[1];
;         float cc[4] = {c01.x, c01.z, c23.x, c23.z}, ss[4] = {c01.y, c01.w, c23.y, c23.w};
;         f32x4 t1 = acc[0][bj][m][n], t2 = acc[1][bj][m][n], o1, o2;
;         #pragma unroll
;         for (int j = 0; j < 4; ++j) { o1[j] = (t1[j] * cc[j] - t2[j] * ss[j]) * sc; o2[j] = (t2[j] * cc[j] + t1[j] * ss[j]) * sc; }
;         long o = (long)tok * td.ldo + (td.brow + i0);
;         uint2 pk; pk.x = pack2(o1[0], o1[1]); pk.y = pack2(o1[2], o1[3]);
;         *(uint2*)(td.outb + o) = pk;
;         pk.x = pack2(o2[0], o2[1]); pk.y = pack2(o2[2], o2[3]);
;         *(uint2*)(td.outb + o + 128) = pk;
;         if (td.outT) {
;           u16* tp = td.outT + (long)i0 * LDT + tok;
;           #pragma unroll
;           for (int j = 0; j < 4; ++j) {
;             tp[(long)j * LDT] = (u16)(pack2(o1[j], 0.f) & 0xffffu);
;             tp[(long)(j + 128) * LDT] = (u16)(pack2(o2[j], 0.f) & 0xffffu);
;           }
.LBB0_612:
	v_add_u32_e32 v132, v147, v132
	v_lshl_add_u64 v[138:139], v[132:133], 3, s[40:41]
	s_and_b64 vcc, exec, s[0:1]
	s_waitcnt vmcnt(14)
	v_mov_b32_e32 v150, v212
	v_mov_b32_e32 v151, v213
	v_mov_b32_e32 v152, v214
	v_mov_b32_e32 v153, v215
	v_mov_b32_e32 v154, v216
	v_mov_b32_e32 v155, v217
	v_mov_b32_e32 v156, v218
	v_mov_b32_e32 v157, v219
	v_mov_b32_e32 v139, v152
	v_mov_b32_e32 v152, v151
	v_mov_b32_e32 v151, v156
	v_mov_b32_e32 v156, v155
	v_mov_b32_e32 v138, v150
	v_mov_b32_e32 v150, v154
	v_pk_mul_f32 v[154:155], v[80:81], v[152:153]
	v_pk_mul_f32 v[152:153], v[16:17], v[152:153]
	v_pk_mul_f32 v[158:159], v[82:83], v[156:157]
	v_pk_mul_f32 v[156:157], v[18:19], v[156:157]
	v_pk_fma_f32 v[154:155], v[16:17], v[138:139], v[154:155]
	v_pk_fma_f32 v[138:139], v[80:81], v[138:139], v[152:153] neg_lo:[0,0,1] neg_hi:[0,0,1]
	v_pk_fma_f32 v[158:159], v[18:19], v[150:151], v[158:159]
	v_pk_fma_f32 v[150:151], v[82:83], v[150:151], v[156:157] neg_lo:[0,0,1] neg_hi:[0,0,1]
	v_pk_mul_f32 v[152:153], v[134:135], v[154:155]
	v_pk_mul_f32 v[154:155], v[134:135], v[138:139]
	v_pk_mul_f32 v[150:151], v[134:135], v[150:151]
	v_pk_mul_f32 v[138:139], v[134:135], v[158:159]
	v_cvt_pk_bf16_f32 v156, v154, v155
	v_cvt_pk_bf16_f32 v157, v150, v151
	v_cvt_pk_bf16_f32 v158, v152, v153
	v_cvt_pk_bf16_f32 v159, v138, v139
	global_store_dwordx2 v[130:131], v[156:157], off offset:32
	global_store_dwordx2 v[130:131], v[158:159], off offset:288
	s_cbranch_vccnz .LBB0_614
	v_lshl_add_u64 v[140:141], v[128:129], 1, v[140:141]
	v_add_co_u32_e32 v156, vcc, 0x400000, v140
	v_cvt_pk_bf16_f32 v132, v154, s0
	s_nop 0
	v_addc_co_u32_e32 v157, vcc, 0, v141, vcc
	global_store_short v[140:141], v132, off offset:288
	v_cvt_pk_bf16_f32 v132, v152, s0
	v_add_co_u32_e32 v154, vcc, 0x8000, v140
	global_store_short v[156:157], v132, off offset:288
	v_cvt_pk_bf16_f32 v132, v155, s0
	v_addc_co_u32_e32 v155, vcc, 0, v141, vcc
	v_add_co_u32_e32 v152, vcc, 0x408000, v140
	global_store_short v[154:155], v132, off offset:288
	v_cvt_pk_bf16_f32 v132, v153, s0
	v_addc_co_u32_e32 v153, vcc, 0, v141, vcc
	global_store_short v[152:153], v132, off offset:288
	v_add_co_u32_e32 v152, vcc, s66, v140
	v_cvt_pk_bf16_f32 v132, v150, s0
	s_nop 0
	v_addc_co_u32_e32 v153, vcc, 0, v141, vcc
	global_store_short v[152:153], v132, off offset:288
	v_add_co_u32_e32 v152, vcc, 0x410000, v140
	v_cvt_pk_bf16_f32 v132, v138, s0
	s_nop 0
	v_addc_co_u32_e32 v153, vcc, 0, v141, vcc
	v_add_co_u32_e32 v150, vcc, 0x18000, v140
	global_store_short v[152:153], v132, off offset:288
	v_cvt_pk_bf16_f32 v132, v151, s0
	v_addc_co_u32_e32 v151, vcc, 0, v141, vcc
	v_add_co_u32_e32 v138, vcc, 0x418000, v140
	global_store_short v[150:151], v132, off offset:288
	v_cvt_pk_bf16_f32 v132, v139, s0
	v_addc_co_u32_e32 v139, vcc, 0, v141, vcc
	global_store_short v[138:139], v132, off offset:288
.LBB0_614:
	v_add_u32_e32 v132, v147, v142
	v_lshl_add_u64 v[142:143], v[132:133], 3, s[40:41]
	s_and_b64 vcc, exec, s[0:1]
	s_waitcnt vmcnt(14)
	v_mov_b32_e32 v138, v220
	v_mov_b32_e32 v139, v221
	v_mov_b32_e32 v140, v222
	v_mov_b32_e32 v141, v223
	v_mov_b32_e32 v150, v224
	v_mov_b32_e32 v151, v225
	v_mov_b32_e32 v152, v226
	v_mov_b32_e32 v153, v227
	v_mov_b32_e32 v143, v140
	v_mov_b32_e32 v140, v139
	v_mov_b32_e32 v139, v152
	v_mov_b32_e32 v152, v151
	v_mov_b32_e32 v142, v138
	v_mov_b32_e32 v138, v150
	v_pk_mul_f32 v[150:151], v[72:73], v[140:141]
	v_pk_mul_f32 v[140:141], v[8:9], v[140:141]
	v_pk_mul_f32 v[154:155], v[74:75], v[152:153]
	v_pk_mul_f32 v[152:153], v[10:11], v[152:153]
	v_pk_fma_f32 v[150:151], v[8:9], v[142:143], v[150:151]
	v_pk_fma_f32 v[140:141], v[72:73], v[142:143], v[140:141] neg_lo:[0,0,1] neg_hi:[0,0,1]
	v_pk_fma_f32 v[152:153], v[74:75], v[138:139], v[152:153] neg_lo:[0,0,1] neg_hi:[0,0,1]
	v_pk_fma_f32 v[154:155], v[10:11], v[138:139], v[154:155]
	v_pk_mul_f32 v[142:143], v[134:135], v[150:151]
	v_pk_mul_f32 v[150:151], v[134:135], v[140:141]
	v_pk_mul_f32 v[140:141], v[134:135], v[152:153]
	v_pk_mul_f32 v[138:139], v[134:135], v[154:155]
	v_cvt_pk_bf16_f32 v152, v150, v151
	v_cvt_pk_bf16_f32 v153, v140, v141
	v_cvt_pk_bf16_f32 v154, v142, v143
	v_cvt_pk_bf16_f32 v155, v138, v139
	global_store_dwordx2 v[130:131], v[152:153], off offset:64
	global_store_dwordx2 v[130:131], v[154:155], off offset:320
	s_cbranch_vccnz .LBB0_616
	v_lshl_add_u64 v[144:145], v[128:129], 1, v[144:145]
	v_add_co_u32_e32 v152, vcc, 0x400000, v144
	v_cvt_pk_bf16_f32 v132, v150, s0
	s_nop 0
	v_addc_co_u32_e32 v153, vcc, 0, v145, vcc
	global_store_short v[144:145], v132, off offset:288
	v_cvt_pk_bf16_f32 v132, v142, s0
	v_add_co_u32_e32 v150, vcc, 0x8000, v144
	global_store_short v[152:153], v132, off offset:288
	v_cvt_pk_bf16_f32 v132, v151, s0
	v_addc_co_u32_e32 v151, vcc, 0, v145, vcc
	v_add_co_u32_e32 v142, vcc, 0x408000, v144
	global_store_short v[150:151], v132, off offset:288
	v_cvt_pk_bf16_f32 v132, v143, s0
	v_addc_co_u32_e32 v143, vcc, 0, v145, vcc
	global_store_short v[142:143], v132, off offset:288
	v_add_co_u32_e32 v142, vcc, s66, v144
	v_cvt_pk_bf16_f32 v132, v140, s0
	s_nop 0
	v_addc_co_u32_e32 v143, vcc, 0, v145, vcc
	global_store_short v[142:143], v132, off offset:288
	v_add_co_u32_e32 v142, vcc, 0x410000, v144
	v_cvt_pk_bf16_f32 v132, v138, s0
	s_nop 0
	v_addc_co_u32_e32 v143, vcc, 0, v145, vcc
	v_add_co_u32_e32 v140, vcc, 0x18000, v144
	global_store_short v[142:143], v132, off offset:288
	v_cvt_pk_bf16_f32 v132, v141, s0
	v_addc_co_u32_e32 v141, vcc, 0, v145, vcc
	v_add_co_u32_e32 v138, vcc, 0x418000, v144
	global_store_short v[140:141], v132, off offset:288
	v_cvt_pk_bf16_f32 v132, v139, s0
	v_addc_co_u32_e32 v139, vcc, 0, v145, vcc
	global_store_short v[138:139], v132, off offset:288
; __device__ __forceinline__ void gemm_tile(const TileDesc& td, char* shm_c, const int wv) {
;     ...
;       int tok = td.bcol + bj * 128 + n * 16 + br_l;
;       int pos = tok & (SEQ - 1);
;       #pragma unroll
;       for (int m = 0; m < 4; ++m) {
;         int i0 = m * 16 + ar_l;
;         const float4* cs = (const float4*)(td.aux + ((long)pos * 128 + i0) * 2);
;         float4 c01 = cs[0], c23 = cs[1];
;         float cc[4] = {c01.x, c01.z, c23.x, c23.z}, ss[4] = {c01.y, c01.w, c23.y, c23.w};
;         f32x4 t1 = acc[0][bj][m][n], t2 = acc[1][bj][m][n], o1, o2;
;         #pragma unroll
;         for (int j = 0; j < 4; ++j) { o1[j] = (t1[j] * cc[j] - t2[j] * ss[j]) * sc; o2[j] = (t2[j] * cc[j] + t1[j] * ss[j]) * sc; }
;         long o = (long)tok * td.ldo + (td.brow + i0);
;         uint2 pk; pk.x = pack2(o1[0], o1[1]); pk.y = pack2(o1[2], o1[3]);
;         *(uint2*)(td.outb + o) = pk;
;         pk.x = pack2(o2[0], o2[1]); pk.y = pack2(o2[2], o2[3]);
;         *(uint2*)(td.outb + o + 128) = pk;
;         if (td.outT) {
;           u16* tp = td.outT + (long)i0 * LDT + tok;
;           #pragma unroll
;           for (int j = 0; j < 4; ++j) {
;             tp[(long)j * LDT] = (u16)(pack2(o1[j], 0.f) & 0xffffu);
;             tp[(long)(j + 128) * LDT] = (u16)(pack2(o2[j], 0.f) & 0xffffu);
;           }
.LBB0_616:
	v_add_u32_e32 v132, v147, v146
	v_lshl_add_u64 v[142:143], v[132:133], 3, s[40:41]
	s_nop 0
	s_and_b64 vcc, exec, s[0:1]
	s_waitcnt vmcnt(14)
	v_mov_b32_e32 v138, v228
	v_mov_b32_e32 v139, v229
	v_mov_b32_e32 v140, v230
	v_mov_b32_e32 v141, v231
	v_mov_b32_e32 v142, v232
	v_mov_b32_e32 v143, v233
	v_mov_b32_e32 v144, v234
	v_mov_b32_e32 v145, v235
	v_mov_b32_e32 v147, v140
	v_mov_b32_e32 v140, v139
	v_mov_b32_e32 v139, v144
	v_mov_b32_e32 v144, v143
	v_mov_b32_e32 v146, v138
	v_mov_b32_e32 v138, v142
	v_pk_mul_f32 v[142:143], v[64:65], v[140:141]
	v_pk_mul_f32 v[140:141], v[0:1], v[140:141]
	v_pk_mul_f32 v[150:151], v[66:67], v[144:145]
	v_pk_mul_f32 v[144:145], v[2:3], v[144:145]
	v_pk_fma_f32 v[142:143], v[0:1], v[146:147], v[142:143]
	v_pk_fma_f32 v[146:147], v[64:65], v[146:147], v[140:141] neg_lo:[0,0,1] neg_hi:[0,0,1]
	v_pk_fma_f32 v[150:151], v[2:3], v[138:139], v[150:151]
	v_pk_fma_f32 v[144:145], v[66:67], v[138:139], v[144:145] neg_lo:[0,0,1] neg_hi:[0,0,1]
	v_pk_mul_f32 v[140:141], v[134:135], v[142:143]
	v_pk_mul_f32 v[142:143], v[134:135], v[146:147]
	v_pk_mul_f32 v[138:139], v[134:135], v[150:151]
	v_pk_mul_f32 v[134:135], v[134:135], v[144:145]
	v_cvt_pk_bf16_f32 v144, v142, v143
	v_cvt_pk_bf16_f32 v145, v134, v135
	v_cvt_pk_bf16_f32 v146, v140, v141
	v_cvt_pk_bf16_f32 v147, v138, v139
	global_store_dwordx2 v[130:131], v[144:145], off offset:96
	global_store_dwordx2 v[130:131], v[146:147], off offset:352
	s_cbranch_vccnz .LBB0_618
	v_lshl_add_u64 v[128:129], v[128:129], 1, v[148:149]
	v_cvt_pk_bf16_f32 v130, v142, s0
	global_store_short v[128:129], v130, off offset:288
	v_add_co_u32_e32 v130, vcc, 0x400000, v128
	v_cvt_pk_bf16_f32 v132, v140, s0
	s_nop 0
	v_addc_co_u32_e32 v131, vcc, 0, v129, vcc
	global_store_short v[130:131], v132, off offset:288
	v_add_co_u32_e32 v130, vcc, 0x8000, v128
	v_cvt_pk_bf16_f32 v132, v143, s0
	s_nop 0
	v_addc_co_u32_e32 v131, vcc, 0, v129, vcc
	global_store_short v[130:131], v132, off offset:288
	v_add_co_u32_e32 v130, vcc, 0x408000, v128
	v_cvt_pk_bf16_f32 v132, v141, s0
	s_nop 0
	v_addc_co_u32_e32 v131, vcc, 0, v129, vcc
	global_store_short v[130:131], v132, off offset:288
	v_add_co_u32_e32 v130, vcc, s66, v128
	v_cvt_pk_bf16_f32 v132, v134, s0
	s_nop 0
	v_addc_co_u32_e32 v131, vcc, 0, v129, vcc
	global_store_short v[130:131], v132, off offset:288
	v_add_co_u32_e32 v130, vcc, 0x410000, v128
	v_cvt_pk_bf16_f32 v132, v138, s0
	s_nop 0
	v_addc_co_u32_e32 v131, vcc, 0, v129, vcc
	global_store_short v[130:131], v132, off offset:288
	v_add_co_u32_e32 v130, vcc, 0x18000, v128
	v_cvt_pk_bf16_f32 v132, v135, s0
	s_nop 0
	v_addc_co_u32_e32 v131, vcc, 0, v129, vcc
	v_add_co_u32_e32 v128, vcc, 0x418000, v128
	global_store_short v[130:131], v132, off offset:288
	v_cvt_pk_bf16_f32 v130, v139, s0
	v_addc_co_u32_e32 v129, vcc, 0, v129, vcc
	global_store_short v[128:129], v130, off offset:288
